# attention: hand-written fast path for unmasked key tiles whose shifted scores stay below 2^64 of the running reference max: bias minus m_run fed as the QK^T MFMA C operand, no rescale (alpha=1), falls
# speedup vs baseline: 1.0045x; 1.0045x over previous
.LBB0_873:
	s_cmpk_eq_i32 s71, 0xffd0
	s_cselect_b64 s[34:35], -1, 0
	s_and_b64 s[4:5], s[34:35], exec
	s_cselect_b32 s84, 0, s71
	s_cmp_gt_i32 s84, s29
	s_cselect_b64 s[4:5], -1, 0
	s_or_b64 s[4:5], s[58:59], s[4:5]
	s_and_b64 vcc, exec, s[4:5]
	s_cbranch_vccnz .LBB0_883
	s_add_i32 s4, s84, 63
	s_cmp_gt_i32 s4, s95
	s_cselect_b64 s[4:5], -1, 0
	s_or_b64 s[4:5], s[34:35], s[4:5]
	s_and_b64 vcc, exec, s[4:5]
	s_cbranch_vccnz .Lattn_orig
	ds_read_b128 v[88:91], v221
	ds_read_b128 v[92:95], v221 offset:64
	ds_read_b128 v[164:167], v221 offset:576
	ds_read_b128 v[168:171], v221 offset:640
	ds_read_b128 v[172:175], v221 offset:4608
	ds_read_b128 v[236:239], v221 offset:4672
	ds_read_b128 v[240:243], v221 offset:5184
	ds_read_b128 v[160:163], v221 offset:5248
	v_pk_add_f32 v[116:117], v[140:141], v[84:85] neg_lo:[0,1] neg_hi:[0,1]
	v_pk_add_f32 v[118:119], v[140:141], v[86:87] neg_lo:[0,1] neg_hi:[0,1]
	v_pk_add_f32 v[100:101], v[142:143], v[84:85] neg_lo:[0,1] neg_hi:[0,1]
	v_pk_add_f32 v[102:103], v[142:143], v[86:87] neg_lo:[0,1] neg_hi:[0,1]
	v_pk_add_f32 v[112:113], v[140:141], v[76:77] neg_lo:[0,1] neg_hi:[0,1]
	v_pk_add_f32 v[114:115], v[140:141], v[78:79] neg_lo:[0,1] neg_hi:[0,1]
	v_pk_add_f32 v[96:97], v[142:143], v[76:77] neg_lo:[0,1] neg_hi:[0,1]
	v_pk_add_f32 v[98:99], v[142:143], v[78:79] neg_lo:[0,1] neg_hi:[0,1]
	v_pk_add_f32 v[108:109], v[140:141], v[80:81] neg_lo:[0,1] neg_hi:[0,1]
	v_pk_add_f32 v[110:111], v[140:141], v[82:83] neg_lo:[0,1] neg_hi:[0,1]
	v_pk_add_f32 v[244:245], v[142:143], v[80:81] neg_lo:[0,1] neg_hi:[0,1]
	v_pk_add_f32 v[246:247], v[142:143], v[82:83] neg_lo:[0,1] neg_hi:[0,1]
	v_pk_add_f32 v[104:105], v[140:141], v[72:73] neg_lo:[0,1] neg_hi:[0,1]
	v_pk_add_f32 v[106:107], v[140:141], v[74:75] neg_lo:[0,1] neg_hi:[0,1]
	v_pk_add_f32 v[248:249], v[142:143], v[72:73] neg_lo:[0,1] neg_hi:[0,1]
	v_pk_add_f32 v[250:251], v[142:143], v[74:75] neg_lo:[0,1] neg_hi:[0,1]
	v_pk_add_f32 v[116:117], v[116:117], v[226:227] op_sel:[0,1] op_sel_hi:[1,1] neg_lo:[0,1] neg_hi:[0,1]
	v_pk_add_f32 v[118:119], v[118:119], v[226:227] op_sel:[0,1] op_sel_hi:[1,1] neg_lo:[0,1] neg_hi:[0,1]
	v_pk_add_f32 v[100:101], v[100:101], v[226:227] op_sel_hi:[1,0] neg_lo:[0,1] neg_hi:[0,1]
	v_pk_add_f32 v[102:103], v[102:103], v[226:227] op_sel_hi:[1,0] neg_lo:[0,1] neg_hi:[0,1]
	v_pk_add_f32 v[112:113], v[112:113], v[226:227] op_sel:[0,1] op_sel_hi:[1,1] neg_lo:[0,1] neg_hi:[0,1]
	v_pk_add_f32 v[114:115], v[114:115], v[226:227] op_sel:[0,1] op_sel_hi:[1,1] neg_lo:[0,1] neg_hi:[0,1]
	v_pk_add_f32 v[96:97], v[96:97], v[226:227] op_sel_hi:[1,0] neg_lo:[0,1] neg_hi:[0,1]
	v_pk_add_f32 v[98:99], v[98:99], v[226:227] op_sel_hi:[1,0] neg_lo:[0,1] neg_hi:[0,1]
	v_pk_add_f32 v[108:109], v[108:109], v[226:227] op_sel:[0,1] op_sel_hi:[1,1] neg_lo:[0,1] neg_hi:[0,1]
	v_pk_add_f32 v[110:111], v[110:111], v[226:227] op_sel:[0,1] op_sel_hi:[1,1] neg_lo:[0,1] neg_hi:[0,1]
	v_pk_add_f32 v[244:245], v[244:245], v[226:227] op_sel_hi:[1,0] neg_lo:[0,1] neg_hi:[0,1]
	v_pk_add_f32 v[246:247], v[246:247], v[226:227] op_sel_hi:[1,0] neg_lo:[0,1] neg_hi:[0,1]
	v_pk_add_f32 v[104:105], v[104:105], v[226:227] op_sel:[0,1] op_sel_hi:[1,1] neg_lo:[0,1] neg_hi:[0,1]
	v_pk_add_f32 v[106:107], v[106:107], v[226:227] op_sel:[0,1] op_sel_hi:[1,1] neg_lo:[0,1] neg_hi:[0,1]
	v_pk_add_f32 v[248:249], v[248:249], v[226:227] op_sel_hi:[1,0] neg_lo:[0,1] neg_hi:[0,1]
	v_pk_add_f32 v[250:251], v[250:251], v[226:227] op_sel_hi:[1,0] neg_lo:[0,1] neg_hi:[0,1]
	s_waitcnt lgkmcnt(4)
	v_mfma_f32_16x16x32_bf16 v[116:119], v[88:91], v[0:3], v[116:119]
	v_mfma_f32_16x16x32_bf16 v[100:103], v[88:91], v[8:11], v[100:103]
	v_mfma_f32_16x16x32_bf16 v[112:115], v[164:167], v[0:3], v[112:115]
	v_mfma_f32_16x16x32_bf16 v[96:99], v[164:167], v[8:11], v[96:99]
	v_mfma_f32_16x16x32_bf16 v[116:119], v[92:95], v[4:7], v[116:119]
	v_mfma_f32_16x16x32_bf16 v[100:103], v[92:95], v[12:15], v[100:103]
	v_mfma_f32_16x16x32_bf16 v[112:115], v[168:171], v[4:7], v[112:115]
	v_mfma_f32_16x16x32_bf16 v[96:99], v[168:171], v[12:15], v[96:99]
	s_waitcnt lgkmcnt(0)
	v_mfma_f32_16x16x32_bf16 v[108:111], v[172:175], v[0:3], v[108:111]
	v_mfma_f32_16x16x32_bf16 v[244:247], v[172:175], v[8:11], v[244:247]
	v_mfma_f32_16x16x32_bf16 v[104:107], v[240:243], v[0:3], v[104:107]
	v_mfma_f32_16x16x32_bf16 v[248:251], v[240:243], v[8:11], v[248:251]
	v_mfma_f32_16x16x32_bf16 v[108:111], v[236:239], v[4:7], v[108:111]
	v_mfma_f32_16x16x32_bf16 v[244:247], v[236:239], v[12:15], v[244:247]
	v_mfma_f32_16x16x32_bf16 v[104:107], v[160:163], v[4:7], v[104:107]
	v_mfma_f32_16x16x32_bf16 v[248:251], v[160:163], v[12:15], v[248:251]
	ds_read_b128 v[88:91], v222 offset:9216
	ds_read_b128 v[92:95], v222 offset:9280
	ds_read_b128 v[164:167], v222 offset:11520
	ds_read_b128 v[168:171], v222 offset:11584
	ds_read_b128 v[172:175], v222 offset:13824
	ds_read_b128 v[236:239], v222 offset:13888
	ds_read_b128 v[240:243], v223 offset:9216
	ds_read_b128 v[160:163], v223 offset:9280
	v_max3_f32 v228, v116, v117, v118
	v_max3_f32 v229, v100, v101, v102
	v_max3_f32 v228, v228, v119, v112
	v_max3_f32 v229, v229, v103, v96
	v_max3_f32 v228, v228, v113, v114
	v_max3_f32 v229, v229, v97, v98
	v_max3_f32 v228, v228, v115, v108
	v_max3_f32 v229, v229, v99, v244
	v_max3_f32 v228, v228, v109, v110
	v_max3_f32 v229, v229, v245, v246
	v_max3_f32 v228, v228, v111, v104
	v_max3_f32 v229, v229, v247, v248
	v_max3_f32 v228, v228, v105, v106
	v_max3_f32 v229, v229, v249, v250
	v_max_f32_e32 v228, v228, v107
	v_max_f32_e32 v229, v229, v251
	v_max_f32_e32 v202, v228, v229
	v_cmp_lt_f32_e32 vcc, 0x42800000, v202
	s_cbranch_vccnz .Lattn_orig
	v_exp_f32_e32 v116, v116
	v_exp_f32_e32 v117, v117
	v_exp_f32_e32 v118, v118
	v_exp_f32_e32 v119, v119
	v_exp_f32_e32 v112, v112
	v_exp_f32_e32 v113, v113
	v_exp_f32_e32 v114, v114
	v_exp_f32_e32 v115, v115
	v_exp_f32_e32 v108, v108
	v_exp_f32_e32 v109, v109
	v_exp_f32_e32 v110, v110
	v_exp_f32_e32 v111, v111
	v_exp_f32_e32 v104, v104
	v_exp_f32_e32 v105, v105
	v_exp_f32_e32 v106, v106
	v_exp_f32_e32 v107, v107
	v_exp_f32_e32 v100, v100
	v_exp_f32_e32 v101, v101
	v_exp_f32_e32 v102, v102
	v_exp_f32_e32 v103, v103
	v_exp_f32_e32 v96, v96
	v_exp_f32_e32 v97, v97
	v_exp_f32_e32 v98, v98
	v_exp_f32_e32 v99, v99
	v_exp_f32_e32 v244, v244
	v_exp_f32_e32 v245, v245
	v_exp_f32_e32 v246, v246
	v_exp_f32_e32 v247, v247
	v_exp_f32_e32 v248, v248
	v_exp_f32_e32 v249, v249
	v_exp_f32_e32 v250, v250
	v_exp_f32_e32 v251, v251
	v_add_f32_e32 v230, 0, v116
	v_add_f32_e32 v231, 0, v100
	v_add_f32_e32 v230, v117, v230
	v_add_f32_e32 v231, v101, v231
	v_add_f32_e32 v230, v118, v230
	v_add_f32_e32 v231, v102, v231
	v_add_f32_e32 v230, v119, v230
	v_add_f32_e32 v231, v103, v231
	v_add_f32_e32 v230, v112, v230
	v_add_f32_e32 v231, v96, v231
	v_add_f32_e32 v230, v113, v230
	v_add_f32_e32 v231, v97, v231
	v_add_f32_e32 v230, v114, v230
	v_add_f32_e32 v231, v98, v231
	v_add_f32_e32 v230, v115, v230
	v_add_f32_e32 v231, v99, v231
	v_add_f32_e32 v230, v108, v230
	v_add_f32_e32 v231, v244, v231
	v_add_f32_e32 v230, v109, v230
	v_add_f32_e32 v231, v245, v231
	v_add_f32_e32 v230, v110, v230
	v_add_f32_e32 v231, v246, v231
	v_add_f32_e32 v230, v111, v230
	v_add_f32_e32 v231, v247, v231
	v_add_f32_e32 v230, v104, v230
	v_add_f32_e32 v231, v248, v231
	v_add_f32_e32 v230, v105, v230
	v_add_f32_e32 v231, v249, v231
	v_add_f32_e32 v230, v106, v230
	v_add_f32_e32 v231, v250, v231
	v_add_f32_e32 v230, v107, v230
	v_add_f32_e32 v231, v251, v231
	v_cvt_pk_bf16_f32 v76, v116, v117
	v_cvt_pk_bf16_f32 v77, v118, v119
	v_cvt_pk_bf16_f32 v78, v112, v113
	v_cvt_pk_bf16_f32 v79, v114, v115
	v_cvt_pk_bf16_f32 v84, v100, v101
	v_cvt_pk_bf16_f32 v85, v102, v103
	v_cvt_pk_bf16_f32 v86, v96, v97
	v_cvt_pk_bf16_f32 v87, v98, v99
	v_cvt_pk_bf16_f32 v72, v108, v109
	v_cvt_pk_bf16_f32 v73, v110, v111
	v_cvt_pk_bf16_f32 v74, v104, v105
	v_cvt_pk_bf16_f32 v75, v106, v107
	v_cvt_pk_bf16_f32 v80, v244, v245
	v_cvt_pk_bf16_f32 v81, v246, v247
	v_cvt_pk_bf16_f32 v82, v248, v249
	v_cvt_pk_bf16_f32 v83, v250, v251
	v_add_f32_e32 v225, v225, v230
	v_add_f32_e32 v224, v224, v231
	s_nop 1
	s_waitcnt lgkmcnt(7)
	v_mfma_f32_16x16x32_bf16 v[52:55], v[88:91], v[76:79], v[52:55]
	v_mfma_f32_16x16x32_bf16 v[36:39], v[88:91], v[84:87], v[36:39]
	s_waitcnt lgkmcnt(6)
	v_mfma_f32_16x16x32_bf16 v[52:55], v[92:95], v[72:75], v[52:55]
	v_mfma_f32_16x16x32_bf16 v[36:39], v[92:95], v[80:83], v[36:39]
	s_waitcnt lgkmcnt(5)
	v_mfma_f32_16x16x32_bf16 v[44:47], v[164:167], v[76:79], v[44:47]
	v_mfma_f32_16x16x32_bf16 v[28:31], v[164:167], v[84:87], v[28:31]
	s_waitcnt lgkmcnt(4)
	v_mfma_f32_16x16x32_bf16 v[44:47], v[168:171], v[72:75], v[44:47]
	v_mfma_f32_16x16x32_bf16 v[28:31], v[168:171], v[80:83], v[28:31]
	s_waitcnt lgkmcnt(3)
	v_mfma_f32_16x16x32_bf16 v[40:43], v[172:175], v[76:79], v[40:43]
	v_mfma_f32_16x16x32_bf16 v[16:19], v[172:175], v[84:87], v[16:19]
	s_waitcnt lgkmcnt(2)
	v_mfma_f32_16x16x32_bf16 v[40:43], v[236:239], v[72:75], v[40:43]
	v_mfma_f32_16x16x32_bf16 v[16:19], v[236:239], v[80:83], v[16:19]
	s_waitcnt lgkmcnt(1)
	v_mfma_f32_16x16x32_bf16 v[48:51], v[240:243], v[76:79], v[48:51]
	v_mfma_f32_16x16x32_bf16 v[32:35], v[240:243], v[84:87], v[32:35]
	s_waitcnt lgkmcnt(0)
	v_mfma_f32_16x16x32_bf16 v[48:51], v[160:163], v[72:75], v[48:51]
	v_mfma_f32_16x16x32_bf16 v[32:35], v[160:163], v[80:83], v[32:35]
	s_branch .LBB0_883
.Lattn_orig:
	ds_read_b128 v[88:91], v221
	ds_read_b128 v[92:95], v221 offset:64
	s_add_i32 s4, s84, 63
	s_cmp_gt_i32 s4, s95
	s_cselect_b64 s[4:5], -1, 0
	s_waitcnt lgkmcnt(1)
	v_mfma_f32_16x16x32_bf16 v[96:99], v[88:91], v[0:3], 0
	s_or_b64 s[74:75], s[34:35], s[4:5]
	s_cmpk_lg_i32 s71, 0xffd0
	s_mov_b64 s[34:35], -1
	v_mfma_f32_16x16x32_bf16 v[88:91], v[88:91], v[8:11], 0
	s_cselect_b64 s[72:73], -1, 0
	s_and_b64 vcc, exec, s[74:75]
	s_waitcnt lgkmcnt(0)
	v_mfma_f32_16x16x32_bf16 v[116:119], v[92:95], v[4:7], v[96:99]
	v_mfma_f32_16x16x32_bf16 v[100:103], v[92:95], v[12:15], v[88:91]
	s_nop 2
	ds_read_b128 v[88:91], v221 offset:576
	ds_read_b128 v[92:95], v221 offset:640
	s_waitcnt lgkmcnt(1)
	v_mfma_f32_16x16x32_bf16 v[96:99], v[88:91], v[0:3], 0
	v_mfma_f32_16x16x32_bf16 v[88:91], v[88:91], v[8:11], 0
	s_waitcnt lgkmcnt(0)
	v_mfma_f32_16x16x32_bf16 v[112:115], v[92:95], v[4:7], v[96:99]
	v_mfma_f32_16x16x32_bf16 v[96:99], v[92:95], v[12:15], v[88:91]
	s_nop 4
	ds_read_b128 v[88:91], v221 offset:4608
	ds_read_b128 v[92:95], v221 offset:4672
	s_waitcnt lgkmcnt(1)
	v_mfma_f32_16x16x32_bf16 v[104:107], v[88:91], v[0:3], 0
	v_mfma_f32_16x16x32_bf16 v[88:91], v[88:91], v[8:11], 0
	s_waitcnt lgkmcnt(0)
	v_mfma_f32_16x16x32_bf16 v[108:111], v[92:95], v[4:7], v[104:107]
	v_mfma_f32_16x16x32_bf16 v[92:95], v[92:95], v[12:15], v[88:91]
	s_nop 4
	ds_read_b128 v[88:91], v221 offset:5184
	ds_read_b128 v[160:163], v221 offset:5248
	s_waitcnt lgkmcnt(1)
	v_mfma_f32_16x16x32_bf16 v[104:107], v[88:91], v[0:3], 0
	v_mfma_f32_16x16x32_bf16 v[88:91], v[88:91], v[8:11], 0
	s_waitcnt lgkmcnt(0)
	v_mfma_f32_16x16x32_bf16 v[104:107], v[160:163], v[4:7], v[104:107]
	v_mfma_f32_16x16x32_bf16 v[88:91], v[160:163], v[12:15], v[88:91]
	s_cbranch_vccnz .LBB0_876
	v_sub_f32_e32 v160, v140, v84
	v_sub_f32_e32 v161, v141, v85
	v_sub_f32_e32 v162, v140, v86
	v_sub_f32_e32 v163, v141, v87
	v_add_f32_e32 v160, v160, v116
	v_add_f32_e32 v161, v161, v117
	v_add_f32_e32 v162, v162, v118
	v_add_f32_e32 v163, v163, v119
	v_max3_f32 v164, v160, s86, v161
	v_max3_f32 v166, v164, v162, v163
	v_sub_f32_e32 v164, v140, v76
	v_sub_f32_e32 v165, v141, v77
	s_mov_b64 s[34:35], 0
	v_add_f32_e32 v164, v164, v112
	v_add_f32_e32 v165, v165, v113
	v_max3_f32 v170, v166, v164, v165
	v_sub_f32_e32 v166, v140, v78
	v_sub_f32_e32 v167, v141, v79
	v_add_f32_e32 v168, v166, v114
	v_add_f32_e32 v169, v167, v115
	v_sub_f32_e32 v166, v140, v80
	v_sub_f32_e32 v167, v141, v81
	v_max3_f32 v170, v170, v168, v169
	v_add_f32_e32 v166, v166, v108
	v_add_f32_e32 v167, v167, v109
	v_max3_f32 v172, v170, v166, v167
	v_sub_f32_e32 v170, v140, v82
	v_sub_f32_e32 v171, v141, v83
	v_add_f32_e32 v170, v170, v110
	v_add_f32_e32 v171, v171, v111
	v_max3_f32 v174, v172, v170, v171
	v_sub_f32_e32 v172, v140, v72
	v_sub_f32_e32 v173, v141, v73
	v_add_f32_e32 v172, v172, v104
	v_add_f32_e32 v173, v173, v105
	v_max3_f32 v202, v174, v172, v173
	v_sub_f32_e32 v174, v140, v74
	v_sub_f32_e32 v175, v141, v75
	v_add_f32_e32 v174, v174, v106
	v_add_f32_e32 v175, v175, v107
	v_max3_f32 v230, v202, v174, v175
